# attention B: PV(map0) MFMAs kept interleaved under map-1 softmax; second tile-sum guard gets its own slow path (re-runs QK1 + softmax1 only)
# baseline (speedup 1.0000x reference)
; #define LAS __attribute__((address_space(3)))
; DI float fast_exp2(float x) { return __builtin_amdgcn_exp2f(x); }
; template <int DQK, int NMAP>
; DI void att_qk(const LAS unsigned char* Kb, int r, int h, const bf16x8 (&qfm)[DQK / NMAP / 16], int mp, f32x16 (&S)[2]) {
;     ...
;         bf16x8 kf[2 * CH];
; #pragma unroll
;         for (int s = 0; s < CH; ++s) { kf[2 * s] = *(const LAS bf16x8*)(kp + 32 * (c * CH + s)); kf[2 * s + 1] = *(const LAS bf16x8*)(kp + 32 * KP + 32 * (c * CH + s)); }
;         __builtin_amdgcn_sched_barrier(0);
;         __builtin_amdgcn_s_setprio(1);
; #pragma unroll
;         for (int s = 0; s < CH; ++s) {
;             if (c == 0 && s == 0) { S[0] = __builtin_amdgcn_mfma_f32_32x32x16_bf16(kf[0], qfm[0], z, 0, 0, 0); S[1] = __builtin_amdgcn_mfma_f32_32x32x16_bf16(kf[1], qfm[0], z, 0, 0, 0); }
;             else { S[0] = __builtin_amdgcn_mfma_f32_32x32x16_bf16(kf[2 * s], qfm[c * CH + s], S[0], 0, 0, 0); S[1] = __builtin_amdgcn_mfma_f32_32x32x16_bf16(kf[2 * s + 1], qfm[c * CH + s], S[1], 0, 0, 0); }
;         }
;         __builtin_amdgcn_s_setprio(0);
;         __builtin_amdgcn_sched_barrier(0);
; DI void att_sm_tail(f32x16 (&S)[2], bf16x8 (&pkm)[2][2], const float mrefm, float& lrunm) {
;     {
;         f32x16& s0 = S[0]; f32x16& s1 = S[1];
;         const f32x2 nm2 = {-mrefm, -mrefm};
;         f32x2 acc2 = {0.f, 0.f};
; #pragma unroll
;         for (int i = 0; i < 16; i += 2) {
;             f32x2 a = {s0[i], s0[i + 1]}, b = {s1[i], s1[i + 1]}; a += nm2; b += nm2;
;             a.x = fast_exp2(a.x); a.y = fast_exp2(a.y); b.x = fast_exp2(b.x); b.y = fast_exp2(b.y);
;             acc2 += a; acc2 += b; s0[i] = a.x; s0[i + 1] = a.y; s1[i] = b.x; s1[i + 1] = b.y;
;         }
;         lrunm += acc2.x + acc2.y;
.LBB0_574:
	s_add_i32 s13, s12, 3
	s_cmp_lt_u32 s13, s9
	s_cselect_b32 s3, s13, s8
	s_lshl_b32 s4, s3, 6
	s_add_i32 s4, s4, s0
	s_cmp_lt_u32 s3, 4
	s_cselect_b32 s4, s1, s4
	s_ashr_i32 s5, s4, 31
	v_lshl_add_u64 v[2:3], s[4:5], 0, v[200:201]
	v_lshl_add_u64 v[6:7], s[4:5], 0, v[202:203]
	v_lshlrev_b64 v[2:3], 9, v[2:3]
	v_mad_u64_u32 v[8:9], s[4:5], v6, s78, v[208:209]
	v_lshl_add_u64 v[2:3], v[206:207], 0, v[2:3]
	v_mad_i32_i24 v9, v7, s78, v9
	global_load_dwordx4 v[2:5], v[2:3], off
	s_cmp_ge_u32 s12, s9
	global_load_dwordx4 v[6:9], v[8:9], off
	s_cbranch_scc1 .LBB0_580
	s_bitcmp1_b32 s12, 0
	s_cselect_b32 s3, 0x2400, 0
	v_add_u32_e32 v0, s3, v244
	ds_read_b128 v[10:13], v0
	ds_read_b128 v[80:83], v0 offset:32
	ds_read_b128 v[84:87], v0 offset:4608
	ds_read_b128 v[88:91], v0 offset:4640
	ds_read_b128 v[188:191], v0 offset:128
	ds_read_b128 v[246:249], v0 offset:4736
	v_mov_b32_e32 v230, 0
	s_mov_b64 exec, 0xffffffff
	v_cvt_pk_bf16_f32 v230, v212, 0
	s_mov_b64 exec, -1
	s_setprio 1
	s_waitcnt lgkmcnt(5)
	v_mfma_f32_32x32x16_bf16 v[112:127], v[10:13], v[156:159], 0
	s_waitcnt lgkmcnt(3)
	v_mfma_f32_32x32x16_bf16 v[128:143], v[84:87], v[156:159], 0
	v_mfma_f32_32x32x16_bf16 v[112:127], v[80:83], v[160:163], v[112:127]
	s_waitcnt lgkmcnt(2)
	v_mfma_f32_32x32x16_bf16 v[128:143], v[88:91], v[160:163], v[128:143]
	s_waitcnt lgkmcnt(1)
	v_mfma_f32_32x32x16_bf16 v[112:127], v[188:191], v[230:233], v[112:127]
	s_waitcnt lgkmcnt(0)
	v_mfma_f32_32x32x16_bf16 v[128:143], v[246:249], v[230:233], v[128:143]
	s_setprio 0
	v_mov_b32_e32 v230, 0
	s_mov_b64 exec, 0xffffffff
	v_cvt_pk_bf16_f32 v230, v210, 0
	s_mov_b64 exec, -1
	ds_read_b128 v[10:13], v0 offset:64
	ds_read_b128 v[180:183], v0 offset:96
	ds_read_b128 v[96:99], v0 offset:4672
	ds_read_b128 v[184:187], v0 offset:4704
	s_setprio 1
	s_waitcnt lgkmcnt(3)
	v_mfma_f32_32x32x16_bf16 v[80:95], v[10:13], v[164:167], 0
	s_waitcnt lgkmcnt(1)
	v_mfma_f32_32x32x16_bf16 v[96:111], v[96:99], v[164:167], 0
	v_mfma_f32_32x32x16_bf16 v[80:95], v[180:183], v[168:171], v[80:95]
	s_waitcnt lgkmcnt(0)
	v_mfma_f32_32x32x16_bf16 v[96:111], v[184:187], v[168:171], v[96:111]
	v_mfma_f32_32x32x16_bf16 v[80:95], v[188:191], v[230:233], v[80:95]
	v_mfma_f32_32x32x16_bf16 v[96:111], v[246:249], v[230:233], v[96:111]
	s_setprio 0
	v_add_u32_e32 v0, v238, v237
	ds_read_b64_tr_b16 v[188:189], v0 offset:18432
	ds_read_b64_tr_b16 v[190:191], v0 offset:19584
	ds_read_b64_tr_b16 v[184:185], v0 offset:20736
	ds_read_b64_tr_b16 v[186:187], v0 offset:21888
	ds_read_b64_tr_b16 v[180:181], v0 offset:23040
	ds_read_b64_tr_b16 v[182:183], v0 offset:24192
	ds_read_b64_tr_b16 v[10:11], v0 offset:25344
	ds_read_b64_tr_b16 v[12:13], v0 offset:26496
	s_nop 1
	v_exp_f32_e32 v14, v112
	v_exp_f32_e32 v15, v113
	v_exp_f32_e32 v112, v128
	v_exp_f32_e32 v113, v129
	v_exp_f32_e32 v114, v114
	v_exp_f32_e32 v115, v115
	v_exp_f32_e32 v128, v130
	v_exp_f32_e32 v129, v131
	v_pk_add_f32 v[130:131], v[14:15], 0 op_sel_hi:[1,0]
	v_exp_f32_e32 v116, v116
	v_exp_f32_e32 v117, v117
	v_pk_add_f32 v[130:131], v[112:113], v[130:131]
	v_exp_f32_e32 v132, v132
	v_exp_f32_e32 v133, v133
	v_pk_add_f32 v[130:131], v[114:115], v[130:131]
	v_exp_f32_e32 v118, v118
	v_exp_f32_e32 v119, v119
	v_pk_add_f32 v[130:131], v[128:129], v[130:131]
	v_exp_f32_e32 v134, v134
	v_exp_f32_e32 v135, v135
	v_pk_add_f32 v[130:131], v[116:117], v[130:131]
	v_exp_f32_e32 v246, v120
	v_exp_f32_e32 v247, v121
	v_pk_add_f32 v[130:131], v[132:133], v[130:131]
	v_exp_f32_e32 v136, v136
	v_exp_f32_e32 v137, v137
	v_pk_add_f32 v[130:131], v[118:119], v[130:131]
	v_exp_f32_e32 v248, v138
	v_exp_f32_e32 v138, v122
	v_exp_f32_e32 v249, v139
	v_exp_f32_e32 v139, v123
	v_pk_add_f32 v[130:131], v[134:135], v[130:131]
	v_pk_add_f32 v[120:121], v[246:247], v[130:131]
	v_exp_f32_e32 v130, v124
	v_exp_f32_e32 v131, v125
	v_pk_add_f32 v[120:121], v[136:137], v[120:121]
	v_exp_f32_e32 v140, v140
	v_exp_f32_e32 v141, v141
	v_pk_add_f32 v[120:121], v[138:139], v[120:121]
	v_exp_f32_e32 v250, v142
	v_exp_f32_e32 v142, v126
	v_exp_f32_e32 v251, v143
	v_exp_f32_e32 v143, v127
	v_pk_add_f32 v[120:121], v[248:249], v[120:121]
	v_pk_add_f32 v[120:121], v[130:131], v[120:121]
	v_cvt_pk_bf16_f32 v122, v116, v117
	v_pk_add_f32 v[120:121], v[140:141], v[120:121]
	v_cvt_pk_bf16_f32 v123, v118, v119
	v_pk_add_f32 v[120:121], v[142:143], v[120:121]
	v_cvt_pk_bf16_f32 v112, v112, v113
	v_pk_add_f32 v[120:121], v[250:251], v[120:121]
	v_cvt_pk_bf16_f32 v113, v128, v129
	v_add_f32_e32 v120, v120, v121
	v_cmp_nge_f32_e32 vcc, 0x43800000, v120
	s_cbranch_vccnz .LB_slow0
; DI unsigned pk2(float lo, float hi) { f32x2 v = {lo, hi}; bf16x2_t b = __builtin_convertvector(v, bf16x2_t); return __builtin_bit_cast(unsigned, b); }
; DI float fast_exp2(float x) { return __builtin_amdgcn_exp2f(x); }
; DI void att_sm_tail(f32x16 (&S)[2], bf16x8 (&pkm)[2][2], const float mrefm, float& lrunm) {
;     {
;         f32x16& s0 = S[0]; f32x16& s1 = S[1];
;         const f32x2 nm2 = {-mrefm, -mrefm};
;         f32x2 acc2 = {0.f, 0.f};
; #pragma unroll
;         for (int i = 0; i < 16; i += 2) {
;             f32x2 a = {s0[i], s0[i + 1]}, b = {s1[i], s1[i + 1]}; a += nm2; b += nm2;
;             a.x = fast_exp2(a.x); a.y = fast_exp2(a.y); b.x = fast_exp2(b.x); b.y = fast_exp2(b.y);
;             acc2 += a; acc2 += b; s0[i] = a.x; s0[i + 1] = a.y; s1[i] = b.x; s1[i + 1] = b.y;
;         }
;         lrunm += acc2.x + acc2.y;
; #pragma unroll
;         for (int s = 0; s < 2; ++s) {
;             u32x4 w0, w1;
;             w0.x = pk2(s0[8 * s + 0], s0[8 * s + 1]); w0.y = pk2(s0[8 * s + 2], s0[8 * s + 3]); w0.z = pk2(s0[8 * s + 4], s0[8 * s + 5]); w0.w = pk2(s0[8 * s + 6], s0[8 * s + 7]);
;             w1.x = pk2(s1[8 * s + 0], s1[8 * s + 1]); w1.y = pk2(s1[8 * s + 2], s1[8 * s + 3]); w1.z = pk2(s1[8 * s + 4], s1[8 * s + 5]); w1.w = pk2(s1[8 * s + 6], s1[8 * s + 7]);
;             pkm[0][s] = __builtin_bit_cast(bf16x8, w0); pkm[1][s] = __builtin_bit_cast(bf16x8, w1);
;         }
;     }
; }
; DI void att_pvmm1(const s16x4 (&lo)[4], const s16x4 (&hi)[4], const bf16x8 (&pkm)[2][2], f32x16& oe) {
; #pragma unroll
;     for (int q = 0; q < 4; ++q) { const bf16x8 vf = (bf16x8){lo[q][0], lo[q][1], lo[q][2], lo[q][3], hi[q][0], hi[q][1], hi[q][2], hi[q][3]};
;         oe = __builtin_amdgcn_mfma_f32_32x32x16_bf16(vf, pkm[q >> 1][q & 1], oe, 0, 0, 0); }
; }
	v_add_f32_e32 v245, v245, v120
	v_cvt_pk_bf16_f32 v120, v14, v15
	v_cvt_pk_bf16_f32 v121, v114, v115
	v_cvt_pk_bf16_f32 v114, v132, v133
	v_cvt_pk_bf16_f32 v115, v134, v135
	v_cvt_pk_bf16_f32 v124, v246, v247
	v_cvt_pk_bf16_f32 v125, v138, v139
	v_cvt_pk_bf16_f32 v126, v130, v131
	v_cvt_pk_bf16_f32 v127, v142, v143
	v_cvt_pk_bf16_f32 v116, v136, v137
	v_cvt_pk_bf16_f32 v117, v248, v249
	v_cvt_pk_bf16_f32 v118, v140, v141
	v_cvt_pk_bf16_f32 v119, v250, v251
	s_waitcnt lgkmcnt(6)
	v_mfma_f32_32x32x16_bf16 v[64:79], v[188:191], v[120:123], v[64:79]
	v_exp_f32_e32 v14, v80
	v_exp_f32_e32 v15, v81
	v_exp_f32_e32 v96, v96
	v_exp_f32_e32 v97, v97
	v_exp_f32_e32 v82, v82
	v_exp_f32_e32 v83, v83
	v_exp_f32_e32 v98, v98
	v_exp_f32_e32 v99, v99
	v_pk_add_f32 v[80:81], v[14:15], 0 op_sel_hi:[1,0]
	v_exp_f32_e32 v84, v84
	v_exp_f32_e32 v85, v85
	v_pk_add_f32 v[80:81], v[96:97], v[80:81]
	v_exp_f32_e32 v100, v100
	v_exp_f32_e32 v101, v101
	v_pk_add_f32 v[80:81], v[82:83], v[80:81]
	v_exp_f32_e32 v86, v86
	v_exp_f32_e32 v87, v87
	v_pk_add_f32 v[80:81], v[98:99], v[80:81]
	v_exp_f32_e32 v102, v102
	v_exp_f32_e32 v103, v103
	v_pk_add_f32 v[80:81], v[84:85], v[80:81]
	v_exp_f32_e32 v88, v88
	v_exp_f32_e32 v89, v89
	v_pk_add_f32 v[80:81], v[100:101], v[80:81]
	v_exp_f32_e32 v104, v104
	v_exp_f32_e32 v105, v105
	v_pk_add_f32 v[80:81], v[86:87], v[80:81]
	s_nop 0
	v_pk_add_f32 v[80:81], v[102:103], v[80:81]
	s_nop 0
	v_pk_add_f32 v[80:81], v[88:89], v[80:81]
	s_nop 0
	v_pk_add_f32 v[80:81], v[104:105], v[80:81]
	s_waitcnt lgkmcnt(4)
	v_mfma_f32_32x32x16_bf16 v[64:79], v[184:187], v[124:127], v[64:79]
	v_exp_f32_e32 v90, v90
	v_exp_f32_e32 v91, v91
	v_exp_f32_e32 v106, v106
	v_exp_f32_e32 v107, v107
	v_exp_f32_e32 v92, v92
	v_exp_f32_e32 v93, v93
	v_exp_f32_e32 v108, v108
	v_exp_f32_e32 v109, v109
	v_pk_add_f32 v[80:81], v[90:91], v[80:81]
	v_exp_f32_e32 v94, v94
	v_exp_f32_e32 v95, v95
	v_pk_add_f32 v[80:81], v[106:107], v[80:81]
	v_exp_f32_e32 v110, v110
	v_exp_f32_e32 v111, v111
	v_pk_add_f32 v[80:81], v[92:93], v[80:81]
	s_nop 0
	v_pk_add_f32 v[80:81], v[108:109], v[80:81]
	s_nop 0
	v_pk_add_f32 v[80:81], v[94:95], v[80:81]
	s_nop 0
	v_pk_add_f32 v[80:81], v[110:111], v[80:81]
	s_nop 0
	v_add_f32_e32 v80, v80, v81
	v_cmp_nge_f32_e32 vcc, 0x43800000, v80
	s_cbranch_vccnz .LB_slowb0
	v_add_f32_e32 v236, v236, v80
	v_cvt_pk_bf16_f32 v80, v14, v15
	v_cvt_pk_bf16_f32 v81, v82, v83
	v_cvt_pk_bf16_f32 v82, v84, v85
	v_cvt_pk_bf16_f32 v83, v86, v87
	v_cvt_pk_bf16_f32 v84, v96, v97
	v_cvt_pk_bf16_f32 v85, v98, v99
	s_waitcnt lgkmcnt(2)
	v_mfma_f32_32x32x16_bf16 v[64:79], v[180:183], v[112:115], v[64:79]
	v_cvt_pk_bf16_f32 v86, v100, v101
	v_cvt_pk_bf16_f32 v87, v102, v103
	v_cvt_pk_bf16_f32 v88, v88, v89
	v_cvt_pk_bf16_f32 v89, v90, v91
	v_cvt_pk_bf16_f32 v90, v92, v93
	v_cvt_pk_bf16_f32 v91, v94, v95
	v_cvt_pk_bf16_f32 v92, v104, v105
	v_cvt_pk_bf16_f32 v93, v106, v107
	v_cvt_pk_bf16_f32 v94, v108, v109
	v_cvt_pk_bf16_f32 v95, v110, v111
	s_waitcnt lgkmcnt(0)
	v_mfma_f32_32x32x16_bf16 v[64:79], v[10:13], v[116:119], v[64:79]
.LB_cont0:
	v_mfma_f32_32x32x16_bf16 v[48:63], v[188:191], v[80:83], v[48:63]
	v_mfma_f32_32x32x16_bf16 v[48:63], v[184:187], v[88:91], v[48:63]
	v_mfma_f32_32x32x16_bf16 v[48:63], v[180:183], v[84:87], v[48:63]
	v_mfma_f32_32x32x16_bf16 v[48:63], v[10:13], v[92:95], v[48:63]
	ds_read_b64_tr_b16 v[10:11], v0 offset:18496
	ds_read_b64_tr_b16 v[12:13], v0 offset:19648
	ds_read_b64_tr_b16 v[96:97], v0 offset:20800
	ds_read_b64_tr_b16 v[98:99], v0 offset:21952
	ds_read_b64_tr_b16 v[100:101], v0 offset:23104
	ds_read_b64_tr_b16 v[102:103], v0 offset:24256
	ds_read_b64_tr_b16 v[104:105], v0 offset:25408
	ds_read_b64_tr_b16 v[106:107], v0 offset:26560
	s_setprio 1
	s_waitcnt lgkmcnt(6)
	v_mfma_f32_32x32x16_bf16 v[32:47], v[10:13], v[120:123], v[32:47]
	v_mfma_f32_32x32x16_bf16 v[16:31], v[10:13], v[80:83], v[16:31]
	s_waitcnt lgkmcnt(4)
	v_mfma_f32_32x32x16_bf16 v[32:47], v[96:99], v[124:127], v[32:47]
	v_mfma_f32_32x32x16_bf16 v[16:31], v[96:99], v[88:91], v[16:31]
	s_waitcnt lgkmcnt(2)
	v_mfma_f32_32x32x16_bf16 v[32:47], v[100:103], v[112:115], v[32:47]
	v_mfma_f32_32x32x16_bf16 v[16:31], v[100:103], v[84:87], v[16:31]
	s_waitcnt lgkmcnt(0)
	v_mfma_f32_32x32x16_bf16 v[32:47], v[104:107], v[116:119], v[32:47]
	v_mfma_f32_32x32x16_bf16 v[16:31], v[104:107], v[92:95], v[16:31]
	s_setprio 0
; DI float fast_exp2(float x) { return __builtin_amdgcn_exp2f(x); }
; DI void att_sm_tail(f32x16 (&S)[2], bf16x8 (&pkm)[2][2], const float mrefm, float& lrunm) {
;     {
;         f32x16& s0 = S[0]; f32x16& s1 = S[1];
;         const f32x2 nm2 = {-mrefm, -mrefm};
;         f32x2 acc2 = {0.f, 0.f};
; #pragma unroll
;         for (int i = 0; i < 16; i += 2) {
;             f32x2 a = {s0[i], s0[i + 1]}, b = {s1[i], s1[i + 1]}; a += nm2; b += nm2;
;             a.x = fast_exp2(a.x); a.y = fast_exp2(a.y); b.x = fast_exp2(b.x); b.y = fast_exp2(b.y);
;             acc2 += a; acc2 += b; s0[i] = a.x; s0[i + 1] = a.y; s1[i] = b.x; s1[i + 1] = b.y;
;         }
;         lrunm += acc2.x + acc2.y;
.LBB0_580:
	s_add_i32 s14, s12, 1
	s_bitcmp1_b32 s14, 0
	s_cselect_b32 s3, 0x2400, 0
	s_add_i32 s3, s3, 0
	s_add_i32 s4, s12, 4
	s_cmp_lt_u32 s12, s76
	s_cselect_b32 s4, s4, s8
	s_lshl_b32 s5, s4, 6
	s_add_i32 s5, s5, s0
	s_cmp_lt_u32 s4, 4
	s_cselect_b32 s4, s1, s5
	s_ashr_i32 s5, s4, 31
	v_lshl_add_u64 v[10:11], s[4:5], 0, v[200:201]
	v_lshlrev_b64 v[10:11], 9, v[10:11]
	v_add3_u32 v0, s3, v239, v240
	v_lshl_add_u64 v[10:11], v[206:207], 0, v[10:11]
	s_waitcnt vmcnt(5)
	ds_write_b128 v0, v[148:151]
	s_waitcnt vmcnt(4)
	ds_write_b128 v242, v[152:155] offset:27648
	s_waitcnt lgkmcnt(0)
	s_barrier
	global_load_dwordx4 v[148:151], v[10:11], off
	v_lshl_add_u64 v[10:11], s[4:5], 0, v[202:203]
	v_mad_u64_u32 v[12:13], s[4:5], v10, s78, v[208:209]
	v_mad_i32_i24 v13, v11, s78, v13
	global_load_dwordx4 v[152:155], v[12:13], off
	s_cmp_ge_u32 s14, s9
	s_cbranch_scc1 .LBB0_586
	v_add_u32_e32 v0, s3, v243
	v_add_u32_e32 v0, v0, v204
	ds_read_b128 v[10:13], v0
	ds_read_b128 v[80:83], v0 offset:32
	ds_read_b128 v[84:87], v0 offset:4608
	ds_read_b128 v[88:91], v0 offset:4640
	ds_read_b128 v[188:191], v0 offset:128
	ds_read_b128 v[246:249], v0 offset:4736
	v_mov_b32_e32 v230, 0
	s_mov_b64 exec, 0xffffffff
	v_cvt_pk_bf16_f32 v230, v212, 0
	s_mov_b64 exec, -1
	s_setprio 1
	s_waitcnt lgkmcnt(5)
	v_mfma_f32_32x32x16_bf16 v[112:127], v[10:13], v[156:159], 0
	s_waitcnt lgkmcnt(3)
	v_mfma_f32_32x32x16_bf16 v[128:143], v[84:87], v[156:159], 0
	v_mfma_f32_32x32x16_bf16 v[112:127], v[80:83], v[160:163], v[112:127]
	s_waitcnt lgkmcnt(2)
	v_mfma_f32_32x32x16_bf16 v[128:143], v[88:91], v[160:163], v[128:143]
	s_waitcnt lgkmcnt(1)
	v_mfma_f32_32x32x16_bf16 v[112:127], v[188:191], v[230:233], v[112:127]
	s_waitcnt lgkmcnt(0)
	v_mfma_f32_32x32x16_bf16 v[128:143], v[246:249], v[230:233], v[128:143]
	s_setprio 0
	v_mov_b32_e32 v230, 0
	s_mov_b64 exec, 0xffffffff
	v_cvt_pk_bf16_f32 v230, v210, 0
	s_mov_b64 exec, -1
	ds_read_b128 v[10:13], v0 offset:64
	ds_read_b128 v[180:183], v0 offset:96
	ds_read_b128 v[96:99], v0 offset:4672
	ds_read_b128 v[184:187], v0 offset:4704
	s_setprio 1
	s_waitcnt lgkmcnt(3)
	v_mfma_f32_32x32x16_bf16 v[80:95], v[10:13], v[164:167], 0
	s_waitcnt lgkmcnt(1)
	v_mfma_f32_32x32x16_bf16 v[96:111], v[96:99], v[164:167], 0
	v_mfma_f32_32x32x16_bf16 v[80:95], v[180:183], v[168:171], v[80:95]
	s_waitcnt lgkmcnt(0)
	v_mfma_f32_32x32x16_bf16 v[96:111], v[184:187], v[168:171], v[96:111]
	v_mfma_f32_32x32x16_bf16 v[80:95], v[188:191], v[230:233], v[80:95]
	v_mfma_f32_32x32x16_bf16 v[96:111], v[246:249], v[230:233], v[96:111]
	s_setprio 0
	v_add_u32_e32 v0, v238, v237
	ds_read_b64_tr_b16 v[190:191], v0 offset:28800
	ds_read_b64_tr_b16 v[180:181], v0 offset:29952
	ds_read_b64_tr_b16 v[182:183], v0 offset:31104
	ds_read_b64_tr_b16 v[10:11], v0 offset:32256
	ds_read_b64_tr_b16 v[188:189], v0 offset:27648
	ds_read_b64_tr_b16 v[12:13], v0 offset:33408
	ds_read_b64_tr_b16 v[184:185], v0 offset:34560
	ds_read_b64_tr_b16 v[186:187], v0 offset:35712
	s_nop 1
	v_exp_f32_e32 v14, v112
	v_exp_f32_e32 v15, v113
	v_exp_f32_e32 v112, v128
	v_exp_f32_e32 v113, v129
	v_exp_f32_e32 v114, v114
	v_exp_f32_e32 v115, v115
	v_exp_f32_e32 v128, v130
	v_exp_f32_e32 v129, v131
	v_pk_add_f32 v[130:131], v[14:15], 0 op_sel_hi:[1,0]
	v_exp_f32_e32 v116, v116
	v_exp_f32_e32 v117, v117
	v_pk_add_f32 v[130:131], v[112:113], v[130:131]
	v_exp_f32_e32 v132, v132
	v_exp_f32_e32 v133, v133
	v_pk_add_f32 v[130:131], v[114:115], v[130:131]
	v_exp_f32_e32 v118, v118
	v_exp_f32_e32 v119, v119
	v_pk_add_f32 v[130:131], v[128:129], v[130:131]
	v_exp_f32_e32 v134, v134
	v_exp_f32_e32 v135, v135
	v_pk_add_f32 v[130:131], v[116:117], v[130:131]
	v_exp_f32_e32 v246, v120
	v_exp_f32_e32 v247, v121
	v_pk_add_f32 v[130:131], v[132:133], v[130:131]
	v_exp_f32_e32 v136, v136
	v_exp_f32_e32 v137, v137
	v_pk_add_f32 v[130:131], v[118:119], v[130:131]
	v_exp_f32_e32 v248, v138
	v_exp_f32_e32 v138, v122
	v_exp_f32_e32 v249, v139
	v_exp_f32_e32 v139, v123
	v_pk_add_f32 v[130:131], v[134:135], v[130:131]
	v_pk_add_f32 v[120:121], v[246:247], v[130:131]
	v_exp_f32_e32 v130, v124
	v_exp_f32_e32 v131, v125
	v_pk_add_f32 v[120:121], v[136:137], v[120:121]
	v_exp_f32_e32 v140, v140
	v_exp_f32_e32 v141, v141
	v_pk_add_f32 v[120:121], v[138:139], v[120:121]
	v_exp_f32_e32 v250, v142
	v_exp_f32_e32 v142, v126
	v_exp_f32_e32 v251, v143
	v_exp_f32_e32 v143, v127
	v_pk_add_f32 v[120:121], v[248:249], v[120:121]
	v_pk_add_f32 v[120:121], v[130:131], v[120:121]
	v_cvt_pk_bf16_f32 v122, v116, v117
	v_pk_add_f32 v[120:121], v[140:141], v[120:121]
	v_cvt_pk_bf16_f32 v123, v118, v119
	v_pk_add_f32 v[120:121], v[142:143], v[120:121]
	v_cvt_pk_bf16_f32 v112, v112, v113
	v_pk_add_f32 v[120:121], v[250:251], v[120:121]
	v_cvt_pk_bf16_f32 v113, v128, v129
	v_add_f32_e32 v120, v120, v121
	v_cmp_nge_f32_e32 vcc, 0x43800000, v120
	s_cbranch_vccnz .LB_slow1
; DI unsigned pk2(float lo, float hi) { f32x2 v = {lo, hi}; bf16x2_t b = __builtin_convertvector(v, bf16x2_t); return __builtin_bit_cast(unsigned, b); }
; DI float fast_exp2(float x) { return __builtin_amdgcn_exp2f(x); }
; DI void att_sm_tail(f32x16 (&S)[2], bf16x8 (&pkm)[2][2], const float mrefm, float& lrunm) {
;     {
;         f32x16& s0 = S[0]; f32x16& s1 = S[1];
;         const f32x2 nm2 = {-mrefm, -mrefm};
;         f32x2 acc2 = {0.f, 0.f};
; #pragma unroll
;         for (int i = 0; i < 16; i += 2) {
;             f32x2 a = {s0[i], s0[i + 1]}, b = {s1[i], s1[i + 1]}; a += nm2; b += nm2;
;             a.x = fast_exp2(a.x); a.y = fast_exp2(a.y); b.x = fast_exp2(b.x); b.y = fast_exp2(b.y);
;             acc2 += a; acc2 += b; s0[i] = a.x; s0[i + 1] = a.y; s1[i] = b.x; s1[i + 1] = b.y;
;         }
;         lrunm += acc2.x + acc2.y;
; #pragma unroll
;         for (int s = 0; s < 2; ++s) {
;             u32x4 w0, w1;
;             w0.x = pk2(s0[8 * s + 0], s0[8 * s + 1]); w0.y = pk2(s0[8 * s + 2], s0[8 * s + 3]); w0.z = pk2(s0[8 * s + 4], s0[8 * s + 5]); w0.w = pk2(s0[8 * s + 6], s0[8 * s + 7]);
;             w1.x = pk2(s1[8 * s + 0], s1[8 * s + 1]); w1.y = pk2(s1[8 * s + 2], s1[8 * s + 3]); w1.z = pk2(s1[8 * s + 4], s1[8 * s + 5]); w1.w = pk2(s1[8 * s + 6], s1[8 * s + 7]);
;             pkm[0][s] = __builtin_bit_cast(bf16x8, w0); pkm[1][s] = __builtin_bit_cast(bf16x8, w1);
;         }
;     }
; }
; DI void att_pvmm1(const s16x4 (&lo)[4], const s16x4 (&hi)[4], const bf16x8 (&pkm)[2][2], f32x16& oe) {
; #pragma unroll
;     for (int q = 0; q < 4; ++q) { const bf16x8 vf = (bf16x8){lo[q][0], lo[q][1], lo[q][2], lo[q][3], hi[q][0], hi[q][1], hi[q][2], hi[q][3]};
;         oe = __builtin_amdgcn_mfma_f32_32x32x16_bf16(vf, pkm[q >> 1][q & 1], oe, 0, 0, 0); }
; }
	v_add_f32_e32 v245, v245, v120
	v_cvt_pk_bf16_f32 v120, v14, v15
	v_cvt_pk_bf16_f32 v121, v114, v115
	v_cvt_pk_bf16_f32 v114, v132, v133
	v_cvt_pk_bf16_f32 v115, v134, v135
	v_cvt_pk_bf16_f32 v124, v246, v247
	v_cvt_pk_bf16_f32 v125, v138, v139
	v_cvt_pk_bf16_f32 v126, v130, v131
	v_cvt_pk_bf16_f32 v127, v142, v143
	v_cvt_pk_bf16_f32 v116, v136, v137
	v_cvt_pk_bf16_f32 v117, v248, v249
	v_cvt_pk_bf16_f32 v118, v140, v141
	v_cvt_pk_bf16_f32 v119, v250, v251
	s_waitcnt lgkmcnt(3)
	v_mfma_f32_32x32x16_bf16 v[64:79], v[188:191], v[120:123], v[64:79]
	v_exp_f32_e32 v14, v80
	v_exp_f32_e32 v15, v81
	v_exp_f32_e32 v96, v96
	v_exp_f32_e32 v97, v97
	v_exp_f32_e32 v82, v82
	v_exp_f32_e32 v83, v83
	v_exp_f32_e32 v98, v98
	v_exp_f32_e32 v99, v99
	v_pk_add_f32 v[80:81], v[14:15], 0 op_sel_hi:[1,0]
	v_exp_f32_e32 v84, v84
	v_exp_f32_e32 v85, v85
	v_pk_add_f32 v[80:81], v[96:97], v[80:81]
	v_exp_f32_e32 v100, v100
	v_exp_f32_e32 v101, v101
	v_pk_add_f32 v[80:81], v[82:83], v[80:81]
	v_exp_f32_e32 v86, v86
	v_exp_f32_e32 v87, v87
	v_pk_add_f32 v[80:81], v[98:99], v[80:81]
	v_exp_f32_e32 v102, v102
	v_exp_f32_e32 v103, v103
	v_pk_add_f32 v[80:81], v[84:85], v[80:81]
	v_exp_f32_e32 v88, v88
	v_exp_f32_e32 v89, v89
	v_pk_add_f32 v[80:81], v[100:101], v[80:81]
	v_exp_f32_e32 v104, v104
	v_exp_f32_e32 v105, v105
	v_pk_add_f32 v[80:81], v[86:87], v[80:81]
	s_nop 0
	v_pk_add_f32 v[80:81], v[102:103], v[80:81]
	s_nop 0
	v_pk_add_f32 v[80:81], v[88:89], v[80:81]
	s_nop 0
	v_pk_add_f32 v[80:81], v[104:105], v[80:81]
	v_mfma_f32_32x32x16_bf16 v[64:79], v[180:183], v[124:127], v[64:79]
	v_exp_f32_e32 v90, v90
	v_exp_f32_e32 v91, v91
	v_exp_f32_e32 v106, v106
	v_exp_f32_e32 v107, v107
	v_exp_f32_e32 v92, v92
	v_exp_f32_e32 v93, v93
	v_exp_f32_e32 v108, v108
	v_exp_f32_e32 v109, v109
	v_pk_add_f32 v[80:81], v[90:91], v[80:81]
	v_exp_f32_e32 v94, v94
	v_exp_f32_e32 v95, v95
	v_pk_add_f32 v[80:81], v[106:107], v[80:81]
	v_exp_f32_e32 v110, v110
	v_exp_f32_e32 v111, v111
	v_pk_add_f32 v[80:81], v[92:93], v[80:81]
	s_nop 0
	v_pk_add_f32 v[80:81], v[108:109], v[80:81]
	s_nop 0
	v_pk_add_f32 v[80:81], v[94:95], v[80:81]
	s_nop 0
	v_pk_add_f32 v[80:81], v[110:111], v[80:81]
	s_nop 0
	v_add_f32_e32 v80, v80, v81
	v_cmp_nge_f32_e32 vcc, 0x43800000, v80
	s_cbranch_vccnz .LB_slowb1
	v_add_f32_e32 v236, v236, v80
	v_cvt_pk_bf16_f32 v80, v14, v15
	v_cvt_pk_bf16_f32 v81, v82, v83
	v_cvt_pk_bf16_f32 v82, v84, v85
	v_cvt_pk_bf16_f32 v83, v86, v87
	v_cvt_pk_bf16_f32 v84, v96, v97
	v_cvt_pk_bf16_f32 v85, v98, v99
	s_waitcnt lgkmcnt(2)
	v_mfma_f32_32x32x16_bf16 v[64:79], v[10:13], v[112:115], v[64:79]
	v_cvt_pk_bf16_f32 v86, v100, v101
	v_cvt_pk_bf16_f32 v87, v102, v103
	v_cvt_pk_bf16_f32 v88, v88, v89
	v_cvt_pk_bf16_f32 v89, v90, v91
	v_cvt_pk_bf16_f32 v90, v92, v93
	v_cvt_pk_bf16_f32 v91, v94, v95
	v_cvt_pk_bf16_f32 v92, v104, v105
	v_cvt_pk_bf16_f32 v93, v106, v107
	v_cvt_pk_bf16_f32 v94, v108, v109
	v_cvt_pk_bf16_f32 v95, v110, v111
	s_waitcnt lgkmcnt(0)
	v_mfma_f32_32x32x16_bf16 v[64:79], v[184:187], v[116:119], v[64:79]
.LB_cont1:
	v_mfma_f32_32x32x16_bf16 v[48:63], v[188:191], v[80:83], v[48:63]
	v_mfma_f32_32x32x16_bf16 v[48:63], v[180:183], v[88:91], v[48:63]
	v_mfma_f32_32x32x16_bf16 v[48:63], v[10:13], v[84:87], v[48:63]
	v_mfma_f32_32x32x16_bf16 v[48:63], v[184:187], v[92:95], v[48:63]
	ds_read_b64_tr_b16 v[12:13], v0 offset:28864
	ds_read_b64_tr_b16 v[96:97], v0 offset:30016
	ds_read_b64_tr_b16 v[98:99], v0 offset:31168
	ds_read_b64_tr_b16 v[100:101], v0 offset:32320
	ds_read_b64_tr_b16 v[10:11], v0 offset:27712
	ds_read_b64_tr_b16 v[102:103], v0 offset:33472
	ds_read_b64_tr_b16 v[104:105], v0 offset:34624
	ds_read_b64_tr_b16 v[106:107], v0 offset:35776
	s_setprio 1
	s_waitcnt lgkmcnt(3)
	v_mfma_f32_32x32x16_bf16 v[32:47], v[10:13], v[120:123], v[32:47]
	v_mfma_f32_32x32x16_bf16 v[16:31], v[10:13], v[80:83], v[16:31]
	v_mfma_f32_32x32x16_bf16 v[32:47], v[96:99], v[124:127], v[32:47]
	v_mfma_f32_32x32x16_bf16 v[16:31], v[96:99], v[88:91], v[16:31]
	s_waitcnt lgkmcnt(2)
	v_mfma_f32_32x32x16_bf16 v[32:47], v[100:103], v[112:115], v[32:47]
	v_mfma_f32_32x32x16_bf16 v[16:31], v[100:103], v[84:87], v[16:31]
	s_waitcnt lgkmcnt(0)
	v_mfma_f32_32x32x16_bf16 v[32:47], v[104:107], v[116:119], v[32:47]
	v_mfma_f32_32x32x16_bf16 v[16:31], v[104:107], v[92:95], v[16:31]
	s_setprio 0
; DI float fast_exp2(float x) { return __builtin_amdgcn_exp2f(x); }
; DI void att_sm_tail(f32x16 (&S)[2], bf16x8 (&pkm)[2][2], const float mrefm, float& lrunm) {
;     {
;         f32x16& s0 = S[0]; f32x16& s1 = S[1];
;         const f32x2 nm2 = {-mrefm, -mrefm};
;         f32x2 acc2 = {0.f, 0.f};
; #pragma unroll
;         for (int i = 0; i < 16; i += 2) {
;             f32x2 a = {s0[i], s0[i + 1]}, b = {s1[i], s1[i + 1]}; a += nm2; b += nm2;
;             a.x = fast_exp2(a.x); a.y = fast_exp2(a.y); b.x = fast_exp2(b.x); b.y = fast_exp2(b.y);
;             acc2 += a; acc2 += b; s0[i] = a.x; s0[i + 1] = a.y; s1[i] = b.x; s1[i + 1] = b.y;
;         }
;         lrunm += acc2.x + acc2.y;
.LBB0_586:
	s_bitcmp1_b32 s12, 0
	s_cselect_b32 s3, 0x2400, 0
	s_add_i32 s3, s3, 0
	s_add_i32 s4, s12, 5
	s_cmp_lt_u32 s4, s9
	s_cselect_b32 s4, s4, s8
	s_lshl_b32 s5, s4, 6
	s_add_i32 s5, s5, s0
	s_cmp_lt_u32 s4, 4
	s_cselect_b32 s4, s1, s5
	s_ashr_i32 s5, s4, 31
	v_lshl_add_u64 v[10:11], s[4:5], 0, v[200:201]
	v_lshlrev_b64 v[10:11], 9, v[10:11]
	v_add3_u32 v0, s3, v239, v240
	v_lshl_add_u64 v[10:11], v[206:207], 0, v[10:11]
	s_waitcnt vmcnt(5)
	ds_write_b128 v0, v[176:179]
	s_waitcnt vmcnt(4)
	ds_write_b128 v242, v[172:175] offset:36864
	s_waitcnt lgkmcnt(0)
	s_barrier
	global_load_dwordx4 v[176:179], v[10:11], off
	v_lshl_add_u64 v[10:11], s[4:5], 0, v[202:203]
	v_mad_u64_u32 v[12:13], s[4:5], v10, s78, v[208:209]
	v_mad_i32_i24 v13, v11, s78, v13
	global_load_dwordx4 v[172:175], v[12:13], off
	s_cmp_ge_u32 s12, s11
	s_cbranch_scc1 .LBB0_592
	v_add_u32_e32 v0, s3, v243
	v_add_u32_e32 v0, v0, v204
	ds_read_b128 v[10:13], v0
	ds_read_b128 v[80:83], v0 offset:32
	ds_read_b128 v[84:87], v0 offset:4608
	ds_read_b128 v[88:91], v0 offset:4640
	ds_read_b128 v[188:191], v0 offset:128
	ds_read_b128 v[246:249], v0 offset:4736
	v_mov_b32_e32 v230, 0
	s_mov_b64 exec, 0xffffffff
	v_cvt_pk_bf16_f32 v230, v212, 0
	s_mov_b64 exec, -1
	s_setprio 1
	s_waitcnt lgkmcnt(5)
	v_mfma_f32_32x32x16_bf16 v[112:127], v[10:13], v[156:159], 0
	s_waitcnt lgkmcnt(3)
	v_mfma_f32_32x32x16_bf16 v[128:143], v[84:87], v[156:159], 0
	v_mfma_f32_32x32x16_bf16 v[112:127], v[80:83], v[160:163], v[112:127]
	s_waitcnt lgkmcnt(2)
	v_mfma_f32_32x32x16_bf16 v[128:143], v[88:91], v[160:163], v[128:143]
	s_waitcnt lgkmcnt(1)
	v_mfma_f32_32x32x16_bf16 v[112:127], v[188:191], v[230:233], v[112:127]
	s_waitcnt lgkmcnt(0)
	v_mfma_f32_32x32x16_bf16 v[128:143], v[246:249], v[230:233], v[128:143]
	s_setprio 0
	v_mov_b32_e32 v230, 0
	s_mov_b64 exec, 0xffffffff
	v_cvt_pk_bf16_f32 v230, v210, 0
	s_mov_b64 exec, -1
	ds_read_b128 v[10:13], v0 offset:64
	ds_read_b128 v[180:183], v0 offset:96
	ds_read_b128 v[96:99], v0 offset:4672
	ds_read_b128 v[184:187], v0 offset:4704
	s_setprio 1
	s_waitcnt lgkmcnt(3)
	v_mfma_f32_32x32x16_bf16 v[80:95], v[10:13], v[164:167], 0
	s_waitcnt lgkmcnt(1)
	v_mfma_f32_32x32x16_bf16 v[96:111], v[96:99], v[164:167], 0
	v_mfma_f32_32x32x16_bf16 v[80:95], v[180:183], v[168:171], v[80:95]
	s_waitcnt lgkmcnt(0)
	v_mfma_f32_32x32x16_bf16 v[96:111], v[184:187], v[168:171], v[96:111]
	v_mfma_f32_32x32x16_bf16 v[80:95], v[188:191], v[230:233], v[80:95]
	v_mfma_f32_32x32x16_bf16 v[96:111], v[246:249], v[230:233], v[96:111]
	s_setprio 0
	v_add_u32_e32 v0, v238, v237
	ds_read_b64_tr_b16 v[188:189], v0 offset:36864
	ds_read_b64_tr_b16 v[190:191], v0 offset:38016
	ds_read_b64_tr_b16 v[184:185], v0 offset:39168
	ds_read_b64_tr_b16 v[186:187], v0 offset:40320
	ds_read_b64_tr_b16 v[180:181], v0 offset:41472
	ds_read_b64_tr_b16 v[182:183], v0 offset:42624
	ds_read_b64_tr_b16 v[10:11], v0 offset:43776
	ds_read_b64_tr_b16 v[12:13], v0 offset:44928
	s_nop 1
	v_exp_f32_e32 v14, v112
	v_exp_f32_e32 v15, v113
	v_exp_f32_e32 v112, v128
	v_exp_f32_e32 v113, v129
	v_exp_f32_e32 v114, v114
	v_exp_f32_e32 v115, v115
	v_exp_f32_e32 v128, v130
	v_exp_f32_e32 v129, v131
	v_pk_add_f32 v[130:131], v[14:15], 0 op_sel_hi:[1,0]
	v_exp_f32_e32 v116, v116
	v_exp_f32_e32 v117, v117
	v_pk_add_f32 v[130:131], v[112:113], v[130:131]
	v_exp_f32_e32 v132, v132
	v_exp_f32_e32 v133, v133
	v_pk_add_f32 v[130:131], v[114:115], v[130:131]
	v_exp_f32_e32 v118, v118
	v_exp_f32_e32 v119, v119
	v_pk_add_f32 v[130:131], v[128:129], v[130:131]
	v_exp_f32_e32 v134, v134
	v_exp_f32_e32 v135, v135
	v_pk_add_f32 v[130:131], v[116:117], v[130:131]
	v_exp_f32_e32 v246, v120
	v_exp_f32_e32 v247, v121
	v_pk_add_f32 v[130:131], v[132:133], v[130:131]
	v_exp_f32_e32 v136, v136
	v_exp_f32_e32 v137, v137
	v_pk_add_f32 v[130:131], v[118:119], v[130:131]
	v_exp_f32_e32 v248, v138
	v_exp_f32_e32 v138, v122
	v_exp_f32_e32 v249, v139
	v_exp_f32_e32 v139, v123
	v_pk_add_f32 v[130:131], v[134:135], v[130:131]
	v_pk_add_f32 v[120:121], v[246:247], v[130:131]
	v_exp_f32_e32 v130, v124
	v_exp_f32_e32 v131, v125
	v_pk_add_f32 v[120:121], v[136:137], v[120:121]
	v_exp_f32_e32 v140, v140
	v_exp_f32_e32 v141, v141
	v_pk_add_f32 v[120:121], v[138:139], v[120:121]
	v_exp_f32_e32 v250, v142
	v_exp_f32_e32 v142, v126
	v_exp_f32_e32 v251, v143
	v_exp_f32_e32 v143, v127
	v_pk_add_f32 v[120:121], v[248:249], v[120:121]
	v_pk_add_f32 v[120:121], v[130:131], v[120:121]
	v_cvt_pk_bf16_f32 v122, v116, v117
	v_pk_add_f32 v[120:121], v[140:141], v[120:121]
	v_cvt_pk_bf16_f32 v123, v118, v119
	v_pk_add_f32 v[120:121], v[142:143], v[120:121]
	v_cvt_pk_bf16_f32 v112, v112, v113
	v_pk_add_f32 v[120:121], v[250:251], v[120:121]
	v_cvt_pk_bf16_f32 v113, v128, v129
	v_add_f32_e32 v120, v120, v121
	v_cmp_nge_f32_e32 vcc, 0x43800000, v120
	s_cbranch_vccnz .LB_slow2
; DI unsigned pk2(float lo, float hi) { f32x2 v = {lo, hi}; bf16x2_t b = __builtin_convertvector(v, bf16x2_t); return __builtin_bit_cast(unsigned, b); }
; DI float fast_exp2(float x) { return __builtin_amdgcn_exp2f(x); }
; DI void att_sm_tail(f32x16 (&S)[2], bf16x8 (&pkm)[2][2], const float mrefm, float& lrunm) {
;     {
;         f32x16& s0 = S[0]; f32x16& s1 = S[1];
;         const f32x2 nm2 = {-mrefm, -mrefm};
;         f32x2 acc2 = {0.f, 0.f};
; #pragma unroll
;         for (int i = 0; i < 16; i += 2) {
;             f32x2 a = {s0[i], s0[i + 1]}, b = {s1[i], s1[i + 1]}; a += nm2; b += nm2;
;             a.x = fast_exp2(a.x); a.y = fast_exp2(a.y); b.x = fast_exp2(b.x); b.y = fast_exp2(b.y);
;             acc2 += a; acc2 += b; s0[i] = a.x; s0[i + 1] = a.y; s1[i] = b.x; s1[i + 1] = b.y;
;         }
;         lrunm += acc2.x + acc2.y;
; #pragma unroll
;         for (int s = 0; s < 2; ++s) {
;             u32x4 w0, w1;
;             w0.x = pk2(s0[8 * s + 0], s0[8 * s + 1]); w0.y = pk2(s0[8 * s + 2], s0[8 * s + 3]); w0.z = pk2(s0[8 * s + 4], s0[8 * s + 5]); w0.w = pk2(s0[8 * s + 6], s0[8 * s + 7]);
;             w1.x = pk2(s1[8 * s + 0], s1[8 * s + 1]); w1.y = pk2(s1[8 * s + 2], s1[8 * s + 3]); w1.z = pk2(s1[8 * s + 4], s1[8 * s + 5]); w1.w = pk2(s1[8 * s + 6], s1[8 * s + 7]);
;             pkm[0][s] = __builtin_bit_cast(bf16x8, w0); pkm[1][s] = __builtin_bit_cast(bf16x8, w1);
;         }
;     }
; }
; DI void att_pvmm1(const s16x4 (&lo)[4], const s16x4 (&hi)[4], const bf16x8 (&pkm)[2][2], f32x16& oe) {
; #pragma unroll
;     for (int q = 0; q < 4; ++q) { const bf16x8 vf = (bf16x8){lo[q][0], lo[q][1], lo[q][2], lo[q][3], hi[q][0], hi[q][1], hi[q][2], hi[q][3]};
;         oe = __builtin_amdgcn_mfma_f32_32x32x16_bf16(vf, pkm[q >> 1][q & 1], oe, 0, 0, 0); }
; }
	v_add_f32_e32 v245, v245, v120
	v_cvt_pk_bf16_f32 v120, v14, v15
	v_cvt_pk_bf16_f32 v121, v114, v115
	v_cvt_pk_bf16_f32 v114, v132, v133
	v_cvt_pk_bf16_f32 v115, v134, v135
	v_cvt_pk_bf16_f32 v124, v246, v247
	v_cvt_pk_bf16_f32 v125, v138, v139
	v_cvt_pk_bf16_f32 v126, v130, v131
	v_cvt_pk_bf16_f32 v127, v142, v143
	v_cvt_pk_bf16_f32 v116, v136, v137
	v_cvt_pk_bf16_f32 v117, v248, v249
	v_cvt_pk_bf16_f32 v118, v140, v141
	v_cvt_pk_bf16_f32 v119, v250, v251
	s_waitcnt lgkmcnt(6)
	v_mfma_f32_32x32x16_bf16 v[64:79], v[188:191], v[120:123], v[64:79]
	v_exp_f32_e32 v14, v80
	v_exp_f32_e32 v15, v81
	v_exp_f32_e32 v96, v96
	v_exp_f32_e32 v97, v97
	v_exp_f32_e32 v82, v82
	v_exp_f32_e32 v83, v83
	v_exp_f32_e32 v98, v98
	v_exp_f32_e32 v99, v99
	v_pk_add_f32 v[80:81], v[14:15], 0 op_sel_hi:[1,0]
	v_exp_f32_e32 v84, v84
	v_exp_f32_e32 v85, v85
	v_pk_add_f32 v[80:81], v[96:97], v[80:81]
	v_exp_f32_e32 v100, v100
	v_exp_f32_e32 v101, v101
	v_pk_add_f32 v[80:81], v[82:83], v[80:81]
	v_exp_f32_e32 v86, v86
	v_exp_f32_e32 v87, v87
	v_pk_add_f32 v[80:81], v[98:99], v[80:81]
	v_exp_f32_e32 v102, v102
	v_exp_f32_e32 v103, v103
	v_pk_add_f32 v[80:81], v[84:85], v[80:81]
	v_exp_f32_e32 v88, v88
	v_exp_f32_e32 v89, v89
	v_pk_add_f32 v[80:81], v[100:101], v[80:81]
	v_exp_f32_e32 v104, v104
	v_exp_f32_e32 v105, v105
	v_pk_add_f32 v[80:81], v[86:87], v[80:81]
	s_nop 0
	v_pk_add_f32 v[80:81], v[102:103], v[80:81]
	s_nop 0
	v_pk_add_f32 v[80:81], v[88:89], v[80:81]
	s_nop 0
	v_pk_add_f32 v[80:81], v[104:105], v[80:81]
	s_waitcnt lgkmcnt(4)
	v_mfma_f32_32x32x16_bf16 v[64:79], v[184:187], v[124:127], v[64:79]
	v_exp_f32_e32 v90, v90
	v_exp_f32_e32 v91, v91
	v_exp_f32_e32 v106, v106
	v_exp_f32_e32 v107, v107
	v_exp_f32_e32 v92, v92
	v_exp_f32_e32 v93, v93
	v_exp_f32_e32 v108, v108
	v_exp_f32_e32 v109, v109
	v_pk_add_f32 v[80:81], v[90:91], v[80:81]
	v_exp_f32_e32 v94, v94
	v_exp_f32_e32 v95, v95
	v_pk_add_f32 v[80:81], v[106:107], v[80:81]
	v_exp_f32_e32 v110, v110
	v_exp_f32_e32 v111, v111
	v_pk_add_f32 v[80:81], v[92:93], v[80:81]
	s_nop 0
	v_pk_add_f32 v[80:81], v[108:109], v[80:81]
	s_nop 0
	v_pk_add_f32 v[80:81], v[94:95], v[80:81]
	s_nop 0
	v_pk_add_f32 v[80:81], v[110:111], v[80:81]
	s_nop 0
	v_add_f32_e32 v80, v80, v81
	v_cmp_nge_f32_e32 vcc, 0x43800000, v80
	s_cbranch_vccnz .LB_slowb2
	v_add_f32_e32 v236, v236, v80
	v_cvt_pk_bf16_f32 v80, v14, v15
	v_cvt_pk_bf16_f32 v81, v82, v83
	v_cvt_pk_bf16_f32 v82, v84, v85
	v_cvt_pk_bf16_f32 v83, v86, v87
	v_cvt_pk_bf16_f32 v84, v96, v97
	v_cvt_pk_bf16_f32 v85, v98, v99
	s_waitcnt lgkmcnt(2)
	v_mfma_f32_32x32x16_bf16 v[64:79], v[180:183], v[112:115], v[64:79]
	v_cvt_pk_bf16_f32 v86, v100, v101
	v_cvt_pk_bf16_f32 v87, v102, v103
	v_cvt_pk_bf16_f32 v88, v88, v89
	v_cvt_pk_bf16_f32 v89, v90, v91
	v_cvt_pk_bf16_f32 v90, v92, v93
	v_cvt_pk_bf16_f32 v91, v94, v95
	v_cvt_pk_bf16_f32 v92, v104, v105
	v_cvt_pk_bf16_f32 v93, v106, v107
	v_cvt_pk_bf16_f32 v94, v108, v109
	v_cvt_pk_bf16_f32 v95, v110, v111
	s_waitcnt lgkmcnt(0)
	v_mfma_f32_32x32x16_bf16 v[64:79], v[10:13], v[116:119], v[64:79]
.LB_cont2:
	v_mfma_f32_32x32x16_bf16 v[48:63], v[188:191], v[80:83], v[48:63]
	v_mfma_f32_32x32x16_bf16 v[48:63], v[184:187], v[88:91], v[48:63]
	v_mfma_f32_32x32x16_bf16 v[48:63], v[180:183], v[84:87], v[48:63]
	v_mfma_f32_32x32x16_bf16 v[48:63], v[10:13], v[92:95], v[48:63]
	ds_read_b64_tr_b16 v[10:11], v0 offset:36928
	ds_read_b64_tr_b16 v[12:13], v0 offset:38080
	ds_read_b64_tr_b16 v[96:97], v0 offset:39232
	ds_read_b64_tr_b16 v[98:99], v0 offset:40384
	ds_read_b64_tr_b16 v[100:101], v0 offset:41536
	ds_read_b64_tr_b16 v[102:103], v0 offset:42688
	ds_read_b64_tr_b16 v[104:105], v0 offset:43840
	ds_read_b64_tr_b16 v[106:107], v0 offset:44992
	s_setprio 1
	s_waitcnt lgkmcnt(6)
	v_mfma_f32_32x32x16_bf16 v[32:47], v[10:13], v[120:123], v[32:47]
	v_mfma_f32_32x32x16_bf16 v[16:31], v[10:13], v[80:83], v[16:31]
	s_waitcnt lgkmcnt(4)
	v_mfma_f32_32x32x16_bf16 v[32:47], v[96:99], v[124:127], v[32:47]
	v_mfma_f32_32x32x16_bf16 v[16:31], v[96:99], v[88:91], v[16:31]
	s_waitcnt lgkmcnt(2)
	v_mfma_f32_32x32x16_bf16 v[32:47], v[100:103], v[112:115], v[32:47]
	v_mfma_f32_32x32x16_bf16 v[16:31], v[100:103], v[84:87], v[16:31]
	s_waitcnt lgkmcnt(0)
	v_mfma_f32_32x32x16_bf16 v[32:47], v[104:107], v[116:119], v[32:47]
	v_mfma_f32_32x32x16_bf16 v[16:31], v[104:107], v[92:95], v[16:31]
	s_setprio 0

; DI float fast_exp2(float x) { return __builtin_amdgcn_exp2f(x); }
; template <int MODE>
; DI void att_sm_head(f32x16 (&S)[2], float& mrefm, float& lrunm, f32x16 (&om)[2], bool latent, const MaskP& mk, int h) {
;     ...
;         float ma = fmaxf(fmaxf(s0[0], s0[1]), s0[2]), mb = fmaxf(fmaxf(s1[0], s1[1]), s1[2]);
; #pragma unroll
;         for (int i = 3; i < 15; i += 2) { ma = fmaxf(fmaxf(ma, s0[i]), s0[i + 1]); mb = fmaxf(fmaxf(mb, s1[i]), s1[i + 1]); }
;         ma = fmaxf(fmaxf(ma, s0[15]), fmaxf(mb, s1[15]));
;         { auto rr = __builtin_amdgcn_permlane32_swap(__float_as_uint(ma), __float_as_uint(ma), false, false); ma = fmaxf(__uint_as_float(rr[0]), __uint_as_float(rr[1])); }
;         const bool uninit = mrefm < -1e29f;
;         const bool need = uninit || (ma - mrefm > 8.0f);
;         if (__any(need)) {
;             const float mnew = need ? ma : mrefm;
;             const float f = uninit ? 1.0f : fast_exp2(mrefm - mnew);
;             mrefm = mnew; lrunm *= f;
; #pragma unroll
;             for (int e = 0; e < 2; ++e)
; #pragma unroll
;                 for (int i = 0; i < 16; ++i) om[e][i] *= f;
;         }
;     }
; }
; DI void att_sm_tail(f32x16 (&S)[2], bf16x8 (&pkm)[2][2], const float mrefm, float& lrunm) {
;     {
;         f32x16& s0 = S[0]; f32x16& s1 = S[1];
;         const f32x2 nm2 = {-mrefm, -mrefm};
;         f32x2 acc2 = {0.f, 0.f};
; #pragma unroll
;         for (int i = 0; i < 16; i += 2) {
;             f32x2 a = {s0[i], s0[i + 1]}, b = {s1[i], s1[i + 1]}; a += nm2; b += nm2;
;             a.x = fast_exp2(a.x); a.y = fast_exp2(a.y); b.x = fast_exp2(b.x); b.y = fast_exp2(b.y);
;             acc2 += a; acc2 += b; s0[i] = a.x; s0[i + 1] = a.y; s1[i] = b.x; s1[i + 1] = b.y;
;         }
;         lrunm += acc2.x + acc2.y;
; #pragma unroll
;         for (int s = 0; s < 2; ++s) {
;             u32x4 w0, w1;
;             w0.x = pk2(s0[8 * s + 0], s0[8 * s + 1]); w0.y = pk2(s0[8 * s + 2], s0[8 * s + 3]); w0.z = pk2(s0[8 * s + 4], s0[8 * s + 5]); w0.w = pk2(s0[8 * s + 6], s0[8 * s + 7]);
;             w1.x = pk2(s1[8 * s + 0], s1[8 * s + 1]); w1.y = pk2(s1[8 * s + 2], s1[8 * s + 3]); w1.z = pk2(s1[8 * s + 4], s1[8 * s + 5]); w1.w = pk2(s1[8 * s + 6], s1[8 * s + 7]);
;             pkm[0][s] = __builtin_bit_cast(bf16x8, w0); pkm[1][s] = __builtin_bit_cast(bf16x8, w1);
;         }
;     }
; }
.LB_slowb0:
	s_bitcmp1_b32 s12, 0
	s_cselect_b32 s3, 0x2400, 0
	v_add_u32_e32 v0, s3, v244
	ds_read_b128 v[10:13], v0 offset:64
	ds_read_b128 v[180:183], v0 offset:96
	ds_read_b128 v[96:99], v0 offset:4672
	ds_read_b128 v[184:187], v0 offset:4704
	s_setprio 1
	s_waitcnt lgkmcnt(3)
	v_mfma_f32_32x32x16_bf16 v[80:95], v[10:13], v[164:167], 0
	s_waitcnt lgkmcnt(1)
	v_mfma_f32_32x32x16_bf16 v[96:111], v[96:99], v[164:167], 0
	v_mfma_f32_32x32x16_bf16 v[80:95], v[180:183], v[168:171], v[80:95]
	s_waitcnt lgkmcnt(0)
	v_mfma_f32_32x32x16_bf16 v[96:111], v[184:187], v[168:171], v[96:111]
	s_setprio 0
	v_add_u32_e32 v0, v238, v237
	ds_read_b64_tr_b16 v[188:189], v0 offset:18432
	ds_read_b64_tr_b16 v[190:191], v0 offset:19584
	ds_read_b64_tr_b16 v[184:185], v0 offset:20736
	ds_read_b64_tr_b16 v[186:187], v0 offset:21888
	ds_read_b64_tr_b16 v[180:181], v0 offset:23040
	ds_read_b64_tr_b16 v[182:183], v0 offset:24192
	ds_read_b64_tr_b16 v[10:11], v0 offset:25344
	ds_read_b64_tr_b16 v[12:13], v0 offset:26496
	s_nop 1
	v_max_f32_e32 v15, v97, v97
	v_max_f32_e32 v230, v96, v96
	v_max_f32_e32 v15, v230, v15
	v_max3_f32 v14, v80, v81, v82
	v_max3_f32 v15, v15, v98, v99
	v_max3_f32 v14, v14, v83, v84
	v_max3_f32 v15, v15, v100, v101
	v_max3_f32 v14, v14, v85, v86
	v_max3_f32 v15, v15, v102, v103
	v_max3_f32 v14, v14, v87, v88
	v_max3_f32 v15, v15, v104, v105
	v_max3_f32 v14, v14, v89, v90
	v_max3_f32 v15, v15, v106, v107
	v_max3_f32 v14, v14, v91, v92
	v_max3_f32 v15, v15, v108, v109
	v_max3_f32 v14, v14, v93, v94
	v_max3_f32 v15, v15, v110, v111
	v_max3_f32 v14, v14, v95, v15
	v_mov_b32_e32 v15, v14
	s_nop 1
	v_permlane32_swap_b32_e32 v14, v15
	v_max_f32_e32 v15, v15, v15
	v_max_f32_e32 v14, v14, v14
	v_max_f32_e32 v14, v14, v15
	v_cvt_pk_bf16_f32 v14, v14, v14
	v_lshlrev_b32_e32 v14, 16, v14
	v_sub_f32_e32 v15, v14, v210
	v_cmp_gt_f32_e64 s[4:5], s22, v210
	v_cmp_lt_f32_e32 vcc, s23, v15
	s_or_b64 vcc, s[4:5], vcc
	s_cbranch_vccz .LB_rescBb0
	v_cndmask_b32_e32 v15, v210, v14, vcc
	v_sub_f32_e32 v14, v210, v15
	v_exp_f32_e32 v14, v14
	v_mov_b32_e32 v210, v15
	v_cndmask_b32_e64 v14, v14, 1.0, s[4:5]
	v_mul_f32_e32 v236, v236, v14
	v_pk_mul_f32 v[62:63], v[62:63], v[14:15] op_sel_hi:[1,0]
	v_pk_mul_f32 v[60:61], v[60:61], v[14:15] op_sel_hi:[1,0]
	v_pk_mul_f32 v[58:59], v[58:59], v[14:15] op_sel_hi:[1,0]
	v_pk_mul_f32 v[56:57], v[56:57], v[14:15] op_sel_hi:[1,0]
	v_pk_mul_f32 v[54:55], v[54:55], v[14:15] op_sel_hi:[1,0]
	v_pk_mul_f32 v[52:53], v[52:53], v[14:15] op_sel_hi:[1,0]
	v_pk_mul_f32 v[50:51], v[50:51], v[14:15] op_sel_hi:[1,0]
	v_pk_mul_f32 v[48:49], v[48:49], v[14:15] op_sel_hi:[1,0]
	v_pk_mul_f32 v[30:31], v[30:31], v[14:15] op_sel_hi:[1,0]
	v_pk_mul_f32 v[28:29], v[28:29], v[14:15] op_sel_hi:[1,0]
	v_pk_mul_f32 v[26:27], v[26:27], v[14:15] op_sel_hi:[1,0]
	v_pk_mul_f32 v[24:25], v[24:25], v[14:15] op_sel_hi:[1,0]
	v_pk_mul_f32 v[22:23], v[22:23], v[14:15] op_sel_hi:[1,0]
	v_pk_mul_f32 v[20:21], v[20:21], v[14:15] op_sel_hi:[1,0]
	v_pk_mul_f32 v[18:19], v[18:19], v[14:15] op_sel_hi:[1,0]
	v_pk_mul_f32 v[16:17], v[16:17], v[14:15] op_sel_hi:[1,0]
.LB_rescBb0:
	v_add_f32_e64 v14, v80, -v210
	v_add_f32_e64 v15, v81, -v210
	v_add_f32_e64 v80, v96, -v210
	v_add_f32_e64 v81, v97, -v210
	v_exp_f32_e32 v14, v14
	v_exp_f32_e32 v15, v15
	v_exp_f32_e32 v96, v80
	v_exp_f32_e32 v97, v81
	v_pk_add_f32 v[82:83], v[82:83], v[210:211] op_sel_hi:[1,0] neg_lo:[0,1] neg_hi:[0,1]
	v_pk_add_f32 v[98:99], v[98:99], v[210:211] op_sel_hi:[1,0] neg_lo:[0,1] neg_hi:[0,1]
	v_exp_f32_e32 v82, v82
	v_exp_f32_e32 v83, v83
	v_exp_f32_e32 v98, v98
	v_exp_f32_e32 v99, v99
	v_pk_add_f32 v[84:85], v[84:85], v[210:211] op_sel_hi:[1,0] neg_lo:[0,1] neg_hi:[0,1]
	v_pk_add_f32 v[80:81], v[14:15], 0 op_sel_hi:[1,0]
	v_pk_add_f32 v[100:101], v[100:101], v[210:211] op_sel_hi:[1,0] neg_lo:[0,1] neg_hi:[0,1]
	v_exp_f32_e32 v84, v84
	v_exp_f32_e32 v85, v85
	v_pk_add_f32 v[80:81], v[96:97], v[80:81]
	v_exp_f32_e32 v100, v100
	v_exp_f32_e32 v101, v101
	v_pk_add_f32 v[86:87], v[86:87], v[210:211] op_sel_hi:[1,0] neg_lo:[0,1] neg_hi:[0,1]
	v_pk_add_f32 v[80:81], v[82:83], v[80:81]
	v_pk_add_f32 v[102:103], v[102:103], v[210:211] op_sel_hi:[1,0] neg_lo:[0,1] neg_hi:[0,1]
	v_exp_f32_e32 v86, v86
	v_exp_f32_e32 v87, v87
	v_pk_add_f32 v[80:81], v[98:99], v[80:81]
	v_exp_f32_e32 v102, v102
	v_exp_f32_e32 v103, v103
	v_pk_add_f32 v[88:89], v[88:89], v[210:211] op_sel_hi:[1,0] neg_lo:[0,1] neg_hi:[0,1]
	v_pk_add_f32 v[80:81], v[84:85], v[80:81]
	v_pk_add_f32 v[104:105], v[104:105], v[210:211] op_sel_hi:[1,0] neg_lo:[0,1] neg_hi:[0,1]
	v_exp_f32_e32 v88, v88
	v_exp_f32_e32 v89, v89
	v_pk_add_f32 v[80:81], v[100:101], v[80:81]
	v_exp_f32_e32 v104, v104
	v_exp_f32_e32 v105, v105
	v_pk_add_f32 v[80:81], v[86:87], v[80:81]
	s_nop 0
	v_pk_add_f32 v[80:81], v[102:103], v[80:81]
	s_nop 0
	v_pk_add_f32 v[80:81], v[88:89], v[80:81]
	s_nop 0
	v_pk_add_f32 v[80:81], v[104:105], v[80:81]
	v_add_f32_e64 v90, v90, -v210
	v_add_f32_e64 v91, v91, -v210
	v_add_f32_e64 v106, v106, -v210
	v_add_f32_e64 v107, v107, -v210
	v_exp_f32_e32 v90, v90
	v_exp_f32_e32 v91, v91
	v_exp_f32_e32 v106, v106
	v_exp_f32_e32 v107, v107
	v_pk_add_f32 v[92:93], v[92:93], v[210:211] op_sel_hi:[1,0] neg_lo:[0,1] neg_hi:[0,1]
	v_pk_add_f32 v[108:109], v[108:109], v[210:211] op_sel_hi:[1,0] neg_lo:[0,1] neg_hi:[0,1]
	v_exp_f32_e32 v92, v92
	v_exp_f32_e32 v93, v93
	v_exp_f32_e32 v108, v108
	v_exp_f32_e32 v109, v109
	v_pk_add_f32 v[94:95], v[94:95], v[210:211] op_sel_hi:[1,0] neg_lo:[0,1] neg_hi:[0,1]
	v_pk_add_f32 v[80:81], v[90:91], v[80:81]
	v_pk_add_f32 v[110:111], v[110:111], v[210:211] op_sel_hi:[1,0] neg_lo:[0,1] neg_hi:[0,1]
	v_exp_f32_e32 v94, v94
	v_exp_f32_e32 v95, v95
	v_pk_add_f32 v[80:81], v[106:107], v[80:81]
	v_exp_f32_e32 v110, v110
	v_exp_f32_e32 v111, v111
	v_pk_add_f32 v[80:81], v[92:93], v[80:81]
	s_nop 0
	v_pk_add_f32 v[80:81], v[108:109], v[80:81]
	s_nop 0
	v_pk_add_f32 v[80:81], v[94:95], v[80:81]
	s_nop 0
	v_pk_add_f32 v[80:81], v[110:111], v[80:81]
	s_nop 0
	v_add_f32_e32 v80, v80, v81
	v_add_f32_e32 v236, v236, v80
	v_cvt_pk_bf16_f32 v80, v14, v15
	v_cvt_pk_bf16_f32 v81, v82, v83
	v_cvt_pk_bf16_f32 v82, v84, v85
	v_cvt_pk_bf16_f32 v83, v86, v87
	v_cvt_pk_bf16_f32 v84, v96, v97
	v_cvt_pk_bf16_f32 v85, v98, v99
	s_waitcnt lgkmcnt(0)
	v_mfma_f32_32x32x16_bf16 v[64:79], v[180:183], v[112:115], v[64:79]
	v_cvt_pk_bf16_f32 v86, v100, v101
	v_cvt_pk_bf16_f32 v87, v102, v103
	v_cvt_pk_bf16_f32 v88, v88, v89
	v_cvt_pk_bf16_f32 v89, v90, v91
	v_cvt_pk_bf16_f32 v90, v92, v93
	v_cvt_pk_bf16_f32 v91, v94, v95
	v_cvt_pk_bf16_f32 v92, v104, v105
	v_cvt_pk_bf16_f32 v93, v106, v107
	v_cvt_pk_bf16_f32 v94, v108, v109
	v_cvt_pk_bf16_f32 v95, v110, v111
	s_waitcnt lgkmcnt(0)
	v_mfma_f32_32x32x16_bf16 v[64:79], v[10:13], v[116:119], v[64:79]
	s_branch .LB_cont0

; DI float fast_exp2(float x) { return __builtin_amdgcn_exp2f(x); }
; template <int MODE>
; DI void att_sm_head(f32x16 (&S)[2], float& mrefm, float& lrunm, f32x16 (&om)[2], bool latent, const MaskP& mk, int h) {
;     ...
;         float ma = fmaxf(fmaxf(s0[0], s0[1]), s0[2]), mb = fmaxf(fmaxf(s1[0], s1[1]), s1[2]);
; #pragma unroll
;         for (int i = 3; i < 15; i += 2) { ma = fmaxf(fmaxf(ma, s0[i]), s0[i + 1]); mb = fmaxf(fmaxf(mb, s1[i]), s1[i + 1]); }
;         ma = fmaxf(fmaxf(ma, s0[15]), fmaxf(mb, s1[15]));
;         { auto rr = __builtin_amdgcn_permlane32_swap(__float_as_uint(ma), __float_as_uint(ma), false, false); ma = fmaxf(__uint_as_float(rr[0]), __uint_as_float(rr[1])); }
;         const bool uninit = mrefm < -1e29f;
;         const bool need = uninit || (ma - mrefm > 8.0f);
;         if (__any(need)) {
;             const float mnew = need ? ma : mrefm;
;             const float f = uninit ? 1.0f : fast_exp2(mrefm - mnew);
;             mrefm = mnew; lrunm *= f;
; #pragma unroll
;             for (int e = 0; e < 2; ++e)
; #pragma unroll
;                 for (int i = 0; i < 16; ++i) om[e][i] *= f;
;         }
;     }
; }
; DI void att_sm_tail(f32x16 (&S)[2], bf16x8 (&pkm)[2][2], const float mrefm, float& lrunm) {
;     {
;         f32x16& s0 = S[0]; f32x16& s1 = S[1];
;         const f32x2 nm2 = {-mrefm, -mrefm};
;         f32x2 acc2 = {0.f, 0.f};
; #pragma unroll
;         for (int i = 0; i < 16; i += 2) {
;             f32x2 a = {s0[i], s0[i + 1]}, b = {s1[i], s1[i + 1]}; a += nm2; b += nm2;
;             a.x = fast_exp2(a.x); a.y = fast_exp2(a.y); b.x = fast_exp2(b.x); b.y = fast_exp2(b.y);
;             acc2 += a; acc2 += b; s0[i] = a.x; s0[i + 1] = a.y; s1[i] = b.x; s1[i + 1] = b.y;
;         }
;         lrunm += acc2.x + acc2.y;
; #pragma unroll
;         for (int s = 0; s < 2; ++s) {
;             u32x4 w0, w1;
;             w0.x = pk2(s0[8 * s + 0], s0[8 * s + 1]); w0.y = pk2(s0[8 * s + 2], s0[8 * s + 3]); w0.z = pk2(s0[8 * s + 4], s0[8 * s + 5]); w0.w = pk2(s0[8 * s + 6], s0[8 * s + 7]);
;             w1.x = pk2(s1[8 * s + 0], s1[8 * s + 1]); w1.y = pk2(s1[8 * s + 2], s1[8 * s + 3]); w1.z = pk2(s1[8 * s + 4], s1[8 * s + 5]); w1.w = pk2(s1[8 * s + 6], s1[8 * s + 7]);
;             pkm[0][s] = __builtin_bit_cast(bf16x8, w0); pkm[1][s] = __builtin_bit_cast(bf16x8, w1);
;         }
;     }
; }
.LB_slowb1:
	v_add_u32_e32 v0, s3, v243
	v_add_u32_e32 v0, v0, v204
	ds_read_b128 v[10:13], v0 offset:64
	ds_read_b128 v[180:183], v0 offset:96
	ds_read_b128 v[96:99], v0 offset:4672
	ds_read_b128 v[184:187], v0 offset:4704
	s_setprio 1
	s_waitcnt lgkmcnt(3)
	v_mfma_f32_32x32x16_bf16 v[80:95], v[10:13], v[164:167], 0
	s_waitcnt lgkmcnt(1)
	v_mfma_f32_32x32x16_bf16 v[96:111], v[96:99], v[164:167], 0
	v_mfma_f32_32x32x16_bf16 v[80:95], v[180:183], v[168:171], v[80:95]
	s_waitcnt lgkmcnt(0)
	v_mfma_f32_32x32x16_bf16 v[96:111], v[184:187], v[168:171], v[96:111]
	s_setprio 0
	v_add_u32_e32 v0, v238, v237
	ds_read_b64_tr_b16 v[190:191], v0 offset:28800
	ds_read_b64_tr_b16 v[180:181], v0 offset:29952
	ds_read_b64_tr_b16 v[182:183], v0 offset:31104
	ds_read_b64_tr_b16 v[10:11], v0 offset:32256
	ds_read_b64_tr_b16 v[188:189], v0 offset:27648
	ds_read_b64_tr_b16 v[12:13], v0 offset:33408
	ds_read_b64_tr_b16 v[184:185], v0 offset:34560
	ds_read_b64_tr_b16 v[186:187], v0 offset:35712
	s_nop 1
	v_max_f32_e32 v15, v97, v97
	v_max_f32_e32 v230, v96, v96
	v_max_f32_e32 v15, v230, v15
	v_max3_f32 v14, v80, v81, v82
	v_max3_f32 v15, v15, v98, v99
	v_max3_f32 v14, v14, v83, v84
	v_max3_f32 v15, v15, v100, v101
	v_max3_f32 v14, v14, v85, v86
	v_max3_f32 v15, v15, v102, v103
	v_max3_f32 v14, v14, v87, v88
	v_max3_f32 v15, v15, v104, v105
	v_max3_f32 v14, v14, v89, v90
	v_max3_f32 v15, v15, v106, v107
	v_max3_f32 v14, v14, v91, v92
	v_max3_f32 v15, v15, v108, v109
	v_max3_f32 v14, v14, v93, v94
	v_max3_f32 v15, v15, v110, v111
	v_max3_f32 v14, v14, v95, v15
	v_mov_b32_e32 v15, v14
	s_nop 1
	v_permlane32_swap_b32_e32 v14, v15
	v_max_f32_e32 v15, v15, v15
	v_max_f32_e32 v14, v14, v14
	v_max_f32_e32 v14, v14, v15
	v_cvt_pk_bf16_f32 v14, v14, v14
	v_lshlrev_b32_e32 v14, 16, v14
	v_sub_f32_e32 v15, v14, v210
	v_cmp_gt_f32_e64 s[4:5], s22, v210
	v_cmp_lt_f32_e32 vcc, s23, v15
	s_or_b64 vcc, s[4:5], vcc
	s_cbranch_vccz .LB_rescBb1
	v_cndmask_b32_e32 v15, v210, v14, vcc
	v_sub_f32_e32 v14, v210, v15
	v_exp_f32_e32 v14, v14
	v_mov_b32_e32 v210, v15
	v_cndmask_b32_e64 v14, v14, 1.0, s[4:5]
	v_mul_f32_e32 v236, v236, v14
	v_pk_mul_f32 v[62:63], v[62:63], v[14:15] op_sel_hi:[1,0]
	v_pk_mul_f32 v[60:61], v[60:61], v[14:15] op_sel_hi:[1,0]
	v_pk_mul_f32 v[58:59], v[58:59], v[14:15] op_sel_hi:[1,0]
	v_pk_mul_f32 v[56:57], v[56:57], v[14:15] op_sel_hi:[1,0]
	v_pk_mul_f32 v[54:55], v[54:55], v[14:15] op_sel_hi:[1,0]
	v_pk_mul_f32 v[52:53], v[52:53], v[14:15] op_sel_hi:[1,0]
	v_pk_mul_f32 v[50:51], v[50:51], v[14:15] op_sel_hi:[1,0]
	v_pk_mul_f32 v[48:49], v[48:49], v[14:15] op_sel_hi:[1,0]
	v_pk_mul_f32 v[30:31], v[30:31], v[14:15] op_sel_hi:[1,0]
	v_pk_mul_f32 v[28:29], v[28:29], v[14:15] op_sel_hi:[1,0]
	v_pk_mul_f32 v[26:27], v[26:27], v[14:15] op_sel_hi:[1,0]
	v_pk_mul_f32 v[24:25], v[24:25], v[14:15] op_sel_hi:[1,0]
	v_pk_mul_f32 v[22:23], v[22:23], v[14:15] op_sel_hi:[1,0]
	v_pk_mul_f32 v[20:21], v[20:21], v[14:15] op_sel_hi:[1,0]
	v_pk_mul_f32 v[18:19], v[18:19], v[14:15] op_sel_hi:[1,0]
	v_pk_mul_f32 v[16:17], v[16:17], v[14:15] op_sel_hi:[1,0]
.LB_rescBb1:
	v_add_f32_e64 v14, v80, -v210
	v_add_f32_e64 v15, v81, -v210
	v_add_f32_e64 v80, v96, -v210
	v_add_f32_e64 v81, v97, -v210
	v_exp_f32_e32 v14, v14
	v_exp_f32_e32 v15, v15
	v_exp_f32_e32 v96, v80
	v_exp_f32_e32 v97, v81
	v_pk_add_f32 v[82:83], v[82:83], v[210:211] op_sel_hi:[1,0] neg_lo:[0,1] neg_hi:[0,1]
	v_pk_add_f32 v[98:99], v[98:99], v[210:211] op_sel_hi:[1,0] neg_lo:[0,1] neg_hi:[0,1]
	v_exp_f32_e32 v82, v82
	v_exp_f32_e32 v83, v83
	v_exp_f32_e32 v98, v98
	v_exp_f32_e32 v99, v99
	v_pk_add_f32 v[84:85], v[84:85], v[210:211] op_sel_hi:[1,0] neg_lo:[0,1] neg_hi:[0,1]
	v_pk_add_f32 v[80:81], v[14:15], 0 op_sel_hi:[1,0]
	v_pk_add_f32 v[100:101], v[100:101], v[210:211] op_sel_hi:[1,0] neg_lo:[0,1] neg_hi:[0,1]
	v_exp_f32_e32 v84, v84
	v_exp_f32_e32 v85, v85
	v_pk_add_f32 v[80:81], v[96:97], v[80:81]
	v_exp_f32_e32 v100, v100
	v_exp_f32_e32 v101, v101
	v_pk_add_f32 v[86:87], v[86:87], v[210:211] op_sel_hi:[1,0] neg_lo:[0,1] neg_hi:[0,1]
	v_pk_add_f32 v[80:81], v[82:83], v[80:81]
	v_pk_add_f32 v[102:103], v[102:103], v[210:211] op_sel_hi:[1,0] neg_lo:[0,1] neg_hi:[0,1]
	v_exp_f32_e32 v86, v86
	v_exp_f32_e32 v87, v87
	v_pk_add_f32 v[80:81], v[98:99], v[80:81]
	v_exp_f32_e32 v102, v102
	v_exp_f32_e32 v103, v103
	v_pk_add_f32 v[88:89], v[88:89], v[210:211] op_sel_hi:[1,0] neg_lo:[0,1] neg_hi:[0,1]
	v_pk_add_f32 v[80:81], v[84:85], v[80:81]
	v_pk_add_f32 v[104:105], v[104:105], v[210:211] op_sel_hi:[1,0] neg_lo:[0,1] neg_hi:[0,1]
	v_exp_f32_e32 v88, v88
	v_exp_f32_e32 v89, v89
	v_pk_add_f32 v[80:81], v[100:101], v[80:81]
	v_exp_f32_e32 v104, v104
	v_exp_f32_e32 v105, v105
	v_pk_add_f32 v[80:81], v[86:87], v[80:81]
	s_nop 0
	v_pk_add_f32 v[80:81], v[102:103], v[80:81]
	s_nop 0
	v_pk_add_f32 v[80:81], v[88:89], v[80:81]
	s_nop 0
	v_pk_add_f32 v[80:81], v[104:105], v[80:81]
	v_add_f32_e64 v90, v90, -v210
	v_add_f32_e64 v91, v91, -v210
	v_add_f32_e64 v106, v106, -v210
	v_add_f32_e64 v107, v107, -v210
	v_exp_f32_e32 v90, v90
	v_exp_f32_e32 v91, v91
	v_exp_f32_e32 v106, v106
	v_exp_f32_e32 v107, v107
	v_pk_add_f32 v[92:93], v[92:93], v[210:211] op_sel_hi:[1,0] neg_lo:[0,1] neg_hi:[0,1]
	v_pk_add_f32 v[108:109], v[108:109], v[210:211] op_sel_hi:[1,0] neg_lo:[0,1] neg_hi:[0,1]
	v_exp_f32_e32 v92, v92
	v_exp_f32_e32 v93, v93
	v_exp_f32_e32 v108, v108
	v_exp_f32_e32 v109, v109
	v_pk_add_f32 v[94:95], v[94:95], v[210:211] op_sel_hi:[1,0] neg_lo:[0,1] neg_hi:[0,1]
	v_pk_add_f32 v[80:81], v[90:91], v[80:81]
	v_pk_add_f32 v[110:111], v[110:111], v[210:211] op_sel_hi:[1,0] neg_lo:[0,1] neg_hi:[0,1]
	v_exp_f32_e32 v94, v94
	v_exp_f32_e32 v95, v95
	v_pk_add_f32 v[80:81], v[106:107], v[80:81]
	v_exp_f32_e32 v110, v110
	v_exp_f32_e32 v111, v111
	v_pk_add_f32 v[80:81], v[92:93], v[80:81]
	s_nop 0
	v_pk_add_f32 v[80:81], v[108:109], v[80:81]
	s_nop 0
	v_pk_add_f32 v[80:81], v[94:95], v[80:81]
	s_nop 0
	v_pk_add_f32 v[80:81], v[110:111], v[80:81]
	s_nop 0
	v_add_f32_e32 v80, v80, v81
	v_add_f32_e32 v236, v236, v80
	v_cvt_pk_bf16_f32 v80, v14, v15
	v_cvt_pk_bf16_f32 v81, v82, v83
	v_cvt_pk_bf16_f32 v82, v84, v85
	v_cvt_pk_bf16_f32 v83, v86, v87
	v_cvt_pk_bf16_f32 v84, v96, v97
	v_cvt_pk_bf16_f32 v85, v98, v99
	s_waitcnt lgkmcnt(0)
	v_mfma_f32_32x32x16_bf16 v[64:79], v[10:13], v[112:115], v[64:79]
	v_cvt_pk_bf16_f32 v86, v100, v101
	v_cvt_pk_bf16_f32 v87, v102, v103
	v_cvt_pk_bf16_f32 v88, v88, v89
	v_cvt_pk_bf16_f32 v89, v90, v91
	v_cvt_pk_bf16_f32 v90, v92, v93
	v_cvt_pk_bf16_f32 v91, v94, v95
	v_cvt_pk_bf16_f32 v92, v104, v105
	v_cvt_pk_bf16_f32 v93, v106, v107
	v_cvt_pk_bf16_f32 v94, v108, v109
	v_cvt_pk_bf16_f32 v95, v110, v111
	s_waitcnt lgkmcnt(0)
	v_mfma_f32_32x32x16_bf16 v[64:79], v[184:187], v[116:119], v[64:79]
	s_branch .LB_cont1

; #define LAS __attribute__((address_space(3)))
; DI float fast_exp2(float x) { return __builtin_amdgcn_exp2f(x); }
; template <int DQK, int NMAP>
; DI void att_qk(const LAS unsigned char* Kb, int r, int h, const bf16x8 (&qfm)[DQK / NMAP / 16], int mp, f32x16 (&S)[2]) {
;     ...
;         bf16x8 kf[2 * CH];
; #pragma unroll
;         for (int s = 0; s < CH; ++s) { kf[2 * s] = *(const LAS bf16x8*)(kp + 32 * (c * CH + s)); kf[2 * s + 1] = *(const LAS bf16x8*)(kp + 32 * KP + 32 * (c * CH + s)); }
;         __builtin_amdgcn_sched_barrier(0);
;         __builtin_amdgcn_s_setprio(1);
; #pragma unroll
;         for (int s = 0; s < CH; ++s) {
;             if (c == 0 && s == 0) { S[0] = __builtin_amdgcn_mfma_f32_32x32x16_bf16(kf[0], qfm[0], z, 0, 0, 0); S[1] = __builtin_amdgcn_mfma_f32_32x32x16_bf16(kf[1], qfm[0], z, 0, 0, 0); }
;             else { S[0] = __builtin_amdgcn_mfma_f32_32x32x16_bf16(kf[2 * s], qfm[c * CH + s], S[0], 0, 0, 0); S[1] = __builtin_amdgcn_mfma_f32_32x32x16_bf16(kf[2 * s + 1], qfm[c * CH + s], S[1], 0, 0, 0); }
;         }
;         __builtin_amdgcn_s_setprio(0);
;         __builtin_amdgcn_sched_barrier(0);
; template <int MODE>
; DI void att_sm_head(f32x16 (&S)[2], float& mrefm, float& lrunm, f32x16 (&om)[2], bool latent, const MaskP& mk, int h) {
;     ...
;         float ma = fmaxf(fmaxf(s0[0], s0[1]), s0[2]), mb = fmaxf(fmaxf(s1[0], s1[1]), s1[2]);
; #pragma unroll
;         for (int i = 3; i < 15; i += 2) { ma = fmaxf(fmaxf(ma, s0[i]), s0[i + 1]); mb = fmaxf(fmaxf(mb, s1[i]), s1[i + 1]); }
;         ma = fmaxf(fmaxf(ma, s0[15]), fmaxf(mb, s1[15]));
;         { auto rr = __builtin_amdgcn_permlane32_swap(__float_as_uint(ma), __float_as_uint(ma), false, false); ma = fmaxf(__uint_as_float(rr[0]), __uint_as_float(rr[1])); }
;         const bool uninit = mrefm < -1e29f;
;         const bool need = uninit || (ma - mrefm > 8.0f);
;         if (__any(need)) {
;             const float mnew = need ? ma : mrefm;
;             const float f = uninit ? 1.0f : fast_exp2(mrefm - mnew);
;             mrefm = mnew; lrunm *= f;
; #pragma unroll
;             for (int e = 0; e < 2; ++e)
; #pragma unroll
;                 for (int i = 0; i < 16; ++i) om[e][i] *= f;
;         }
.LB_slowb2:
	v_add_u32_e32 v0, s3, v243
	v_add_u32_e32 v0, v0, v204
	ds_read_b128 v[10:13], v0 offset:64
	ds_read_b128 v[180:183], v0 offset:96
	ds_read_b128 v[96:99], v0 offset:4672
	ds_read_b128 v[184:187], v0 offset:4704
	s_setprio 1
	s_waitcnt lgkmcnt(3)
	v_mfma_f32_32x32x16_bf16 v[80:95], v[10:13], v[164:167], 0
	s_waitcnt lgkmcnt(1)
	v_mfma_f32_32x32x16_bf16 v[96:111], v[96:99], v[164:167], 0
	v_mfma_f32_32x32x16_bf16 v[80:95], v[180:183], v[168:171], v[80:95]
	s_waitcnt lgkmcnt(0)
	v_mfma_f32_32x32x16_bf16 v[96:111], v[184:187], v[168:171], v[96:111]
	s_setprio 0
	v_add_u32_e32 v0, v238, v237
	ds_read_b64_tr_b16 v[188:189], v0 offset:36864
	ds_read_b64_tr_b16 v[190:191], v0 offset:38016
	ds_read_b64_tr_b16 v[184:185], v0 offset:39168
	ds_read_b64_tr_b16 v[186:187], v0 offset:40320
	ds_read_b64_tr_b16 v[180:181], v0 offset:41472
	ds_read_b64_tr_b16 v[182:183], v0 offset:42624
	ds_read_b64_tr_b16 v[10:11], v0 offset:43776
	ds_read_b64_tr_b16 v[12:13], v0 offset:44928
	s_nop 1
	v_max_f32_e32 v15, v97, v97
	v_max_f32_e32 v230, v96, v96
	v_max_f32_e32 v15, v230, v15
	v_max3_f32 v14, v80, v81, v82
	v_max3_f32 v15, v15, v98, v99
	v_max3_f32 v14, v14, v83, v84
	v_max3_f32 v15, v15, v100, v101
	v_max3_f32 v14, v14, v85, v86
	v_max3_f32 v15, v15, v102, v103
	v_max3_f32 v14, v14, v87, v88
	v_max3_f32 v15, v15, v104, v105
	v_max3_f32 v14, v14, v89, v90
	v_max3_f32 v15, v15, v106, v107
	v_max3_f32 v14, v14, v91, v92
	v_max3_f32 v15, v15, v108, v109
	v_max3_f32 v14, v14, v93, v94
	v_max3_f32 v15, v15, v110, v111
	v_max3_f32 v14, v14, v95, v15
	v_mov_b32_e32 v15, v14
	s_nop 1
	v_permlane32_swap_b32_e32 v14, v15
	v_max_f32_e32 v15, v15, v15
	v_max_f32_e32 v14, v14, v14
	v_max_f32_e32 v14, v14, v15
	v_cvt_pk_bf16_f32 v14, v14, v14
	v_lshlrev_b32_e32 v14, 16, v14
	v_sub_f32_e32 v15, v14, v210
	v_cmp_gt_f32_e64 s[4:5], s22, v210
	v_cmp_lt_f32_e32 vcc, s23, v15
	s_or_b64 vcc, s[4:5], vcc
	s_cbranch_vccz .LB_rescBb2
	v_cndmask_b32_e32 v15, v210, v14, vcc
	v_sub_f32_e32 v14, v210, v15
	v_exp_f32_e32 v14, v14
	v_mov_b32_e32 v210, v15
	v_cndmask_b32_e64 v14, v14, 1.0, s[4:5]
	v_mul_f32_e32 v236, v236, v14
	v_pk_mul_f32 v[62:63], v[62:63], v[14:15] op_sel_hi:[1,0]
	v_pk_mul_f32 v[60:61], v[60:61], v[14:15] op_sel_hi:[1,0]
	v_pk_mul_f32 v[58:59], v[58:59], v[14:15] op_sel_hi:[1,0]
	v_pk_mul_f32 v[56:57], v[56:57], v[14:15] op_sel_hi:[1,0]
	v_pk_mul_f32 v[54:55], v[54:55], v[14:15] op_sel_hi:[1,0]
	v_pk_mul_f32 v[52:53], v[52:53], v[14:15] op_sel_hi:[1,0]
	v_pk_mul_f32 v[50:51], v[50:51], v[14:15] op_sel_hi:[1,0]
	v_pk_mul_f32 v[48:49], v[48:49], v[14:15] op_sel_hi:[1,0]
	v_pk_mul_f32 v[30:31], v[30:31], v[14:15] op_sel_hi:[1,0]
	v_pk_mul_f32 v[28:29], v[28:29], v[14:15] op_sel_hi:[1,0]
	v_pk_mul_f32 v[26:27], v[26:27], v[14:15] op_sel_hi:[1,0]
	v_pk_mul_f32 v[24:25], v[24:25], v[14:15] op_sel_hi:[1,0]
	v_pk_mul_f32 v[22:23], v[22:23], v[14:15] op_sel_hi:[1,0]
	v_pk_mul_f32 v[20:21], v[20:21], v[14:15] op_sel_hi:[1,0]
	v_pk_mul_f32 v[18:19], v[18:19], v[14:15] op_sel_hi:[1,0]
	v_pk_mul_f32 v[16:17], v[16:17], v[14:15] op_sel_hi:[1,0]
